# diff-attn: table-driven tile order, LDS-DMA pieces of next pair issued inside stage D MFMAs instead of after barrier
# speedup vs baseline: 1.0063x; 1.0063x over previous
.LBB0_317:
	v_add_f32_e32 v124, 0, v159
	v_add_f32_e32 v124, v171, v124
	v_add_f32_e32 v124, v172, v124
	v_add_f32_e32 v124, v173, v124
	v_add_f32_e32 v124, v174, v124
	v_add_f32_e32 v124, v175, v124
	v_add_f32_e32 v124, v176, v124
	v_add_f32_e32 v124, v177, v124
	v_add_f32_e32 v124, v178, v124
	v_add_f32_e32 v124, v179, v124
	v_add_f32_e32 v124, v180, v124
	v_add_f32_e32 v124, v181, v124
	v_add_f32_e32 v124, v182, v124
	v_add_f32_e32 v124, v183, v124
	v_add_f32_e32 v124, v184, v124
	v_add_f32_e32 v124, v185, v124
	v_add_f32_e32 v124, v124, v186
	v_add_f32_e32 v124, v187, v124
	v_add_f32_e32 v124, v188, v124
	v_add_f32_e32 v124, v189, v124
	v_add_f32_e32 v124, v190, v124
	v_add_f32_e32 v124, v191, v124
	v_add_f32_e32 v124, v192, v124
	v_add_f32_e32 v124, v193, v124
	v_add_f32_e32 v124, v194, v124
	v_add_f32_e32 v124, v195, v124
	v_add_f32_e32 v124, v196, v124
	v_add_f32_e32 v124, v197, v124
	v_add_f32_e32 v124, v198, v124
	v_exp_f32_e32 v80, v80
	v_add_f32_e32 v124, v199, v124
	v_exp_f32_e32 v81, v81
	v_add_f32_e32 v124, v200, v124
	v_exp_f32_e32 v82, v82
	v_add_f32_e32 v124, v201, v124
	v_exp_f32_e32 v83, v83
	v_add_f32_e32 v124, v124, v80
	v_exp_f32_e32 v84, v84
	v_add_f32_e32 v124, v81, v124
	v_exp_f32_e32 v85, v85
	v_add_f32_e32 v124, v82, v124
	v_exp_f32_e32 v86, v86
	v_add_f32_e32 v124, v83, v124
	v_exp_f32_e32 v87, v87
	v_add_f32_e32 v124, v84, v124
	v_exp_f32_e32 v88, v88
	v_add_f32_e32 v124, v85, v124
	v_exp_f32_e32 v89, v89
	v_add_f32_e32 v124, v86, v124
	v_exp_f32_e32 v90, v90
	v_add_f32_e32 v124, v87, v124
	v_exp_f32_e32 v91, v91
	v_add_f32_e32 v124, v88, v124
	v_exp_f32_e32 v125, v92
	v_add_f32_e32 v124, v89, v124
	v_exp_f32_e32 v126, v93
	v_add_f32_e32 v124, v90, v124
	v_exp_f32_e32 v127, v94
	v_add_f32_e32 v124, v91, v124
	v_exp_f32_e32 v159, v95
	v_add_f32_e32 v92, v125, v124
	v_add_f32_e32 v92, v126, v92
	v_add_f32_e32 v92, v127, v92
	v_add_f32_e32 v124, v159, v92
	v_cvt_pk_bf16_f32 v92, v80, v81
	v_cvt_pk_bf16_f32 v93, v82, v83
	v_cvt_pk_bf16_f32 v94, v84, v85
	v_cvt_pk_bf16_f32 v95, v86, v87
	v_cvt_pk_bf16_f32 v88, v88, v89
	v_cvt_pk_bf16_f32 v89, v90, v91
	v_cvt_pk_bf16_f32 v90, v125, v126
	v_cvt_pk_bf16_f32 v91, v127, v159
	s_waitcnt lgkmcnt(14)
	v_mfma_f32_32x32x16_bf16 v[0:15], v[144:147], v[92:95], v[0:15]
	ds_read_b64_tr_b16 v[80:81], v202 offset:18432
	ds_read_b64_tr_b16 v[82:83], v202 offset:18944
	v_exp_f32_e32 v144, v64
	v_exp_f32_e32 v145, v65
	v_add_f32_e32 v64, v124, v144
	v_add_f32_e32 v64, v145, v64
	s_waitcnt lgkmcnt(14)
	v_mfma_f32_32x32x16_bf16 v[0:15], v[140:143], v[88:91], v[0:15]
	ds_read_b64_tr_b16 v[84:85], v202 offset:19456
	ds_read_b64_tr_b16 v[86:87], v202 offset:19968
	v_exp_f32_e32 v140, v66
	v_exp_f32_e32 v141, v67
	v_add_f32_e32 v64, v140, v64
	v_add_f32_e32 v124, v141, v64
	s_waitcnt lgkmcnt(14)
	v_mfma_f32_32x32x16_bf16 v[16:31], v[136:139], v[92:95], v[16:31]
	ds_read_b64_tr_b16 v[64:65], v202 offset:22528
	ds_read_b64_tr_b16 v[66:67], v202 offset:23040
	v_exp_f32_e32 v136, v68
	v_exp_f32_e32 v137, v69
	v_add_f32_e32 v68, v136, v124
	v_add_f32_e32 v68, v137, v68
	s_waitcnt lgkmcnt(14)
	v_mfma_f32_32x32x16_bf16 v[16:31], v[132:135], v[88:91], v[16:31]
	ds_read_b64_tr_b16 v[124:125], v202 offset:23552
	ds_read_b64_tr_b16 v[126:127], v202 offset:24064
	v_exp_f32_e32 v132, v70
	v_exp_f32_e32 v133, v71
	v_add_f32_e32 v68, v132, v68
	v_add_f32_e32 v134, v133, v68
	s_waitcnt lgkmcnt(14)
	v_mfma_f32_32x32x16_bf16 v[32:47], v[128:131], v[92:95], v[32:47]
	ds_read_b64_tr_b16 v[68:69], v202 offset:26624
	ds_read_b64_tr_b16 v[70:71], v202 offset:27136
	v_exp_f32_e32 v128, v72
	v_exp_f32_e32 v129, v73
	v_add_f32_e32 v72, v128, v134
	v_add_f32_e32 v72, v129, v72
	s_waitcnt lgkmcnt(14)
	v_mfma_f32_32x32x16_bf16 v[32:47], v[120:123], v[88:91], v[32:47]
	ds_read_b64_tr_b16 v[120:121], v202 offset:27648
	ds_read_b64_tr_b16 v[122:123], v202 offset:28160
	v_exp_f32_e32 v130, v74
	v_exp_f32_e32 v131, v75
	v_add_f32_e32 v72, v130, v72
	v_add_f32_e32 v134, v131, v72
	s_waitcnt lgkmcnt(14)
	v_mfma_f32_32x32x16_bf16 v[48:63], v[116:119], v[92:95], v[48:63]
	ds_read_b64_tr_b16 v[72:73], v202 offset:30720
	ds_read_b64_tr_b16 v[74:75], v202 offset:31232
	v_exp_f32_e32 v94, v76
	v_exp_f32_e32 v95, v77
	v_add_f32_e32 v76, v94, v134
	v_add_f32_e32 v76, v95, v76
	s_waitcnt lgkmcnt(14)
	v_mfma_f32_32x32x16_bf16 v[48:63], v[112:115], v[88:91], v[48:63]
	v_exp_f32_e32 v113, v78
	ds_read_b64_tr_b16 v[88:89], v202 offset:31744
	ds_read_b64_tr_b16 v[90:91], v202 offset:32256
	v_exp_f32_e32 v114, v79
	v_add_f32_e32 v76, v113, v76
	v_add_f32_e32 v112, v114, v76
	v_cvt_pk_bf16_f32 v76, v144, v145
	v_cvt_pk_bf16_f32 v77, v140, v141
	v_cvt_pk_bf16_f32 v78, v136, v137
	v_cvt_pk_bf16_f32 v79, v132, v133
	v_cvt_pk_bf16_f32 v92, v128, v129
	v_cvt_pk_bf16_f32 v93, v130, v131
	v_cvt_pk_bf16_f32 v94, v94, v95
	v_cvt_pk_bf16_f32 v95, v113, v114
	s_waitcnt lgkmcnt(14)
	v_mfma_f32_32x32x16_bf16 v[0:15], v[80:83], v[76:79], v[0:15]
	s_waitcnt lgkmcnt(10)
	v_mfma_f32_32x32x16_bf16 v[16:31], v[64:67], v[76:79], v[16:31]
	s_waitcnt lgkmcnt(6)
	v_mfma_f32_32x32x16_bf16 v[32:47], v[68:71], v[76:79], v[32:47]
	s_waitcnt lgkmcnt(2)
	v_mfma_f32_32x32x16_bf16 v[48:63], v[72:75], v[76:79], v[48:63]
	v_mfma_f32_32x32x16_bf16 v[0:15], v[84:87], v[92:95], v[0:15]
	v_mfma_f32_32x32x16_bf16 v[16:31], v[124:127], v[92:95], v[16:31]
	v_mfma_f32_32x32x16_bf16 v[32:47], v[120:123], v[92:95], v[32:47]
	s_waitcnt lgkmcnt(0)
	v_mfma_f32_32x32x16_bf16 v[48:63], v[88:91], v[92:95], v[48:63]
	s_andn2_b64 vcc, exec, s[26:27]
	s_cbranch_vccnz .LBB0_350
	s_min_i32 s3, s36, s37
	v_lshl_add_u64 v[128:129], s[24:25], 0, v[230:231]
	s_or_b32 s24, s33, s48
	s_lshl_b32 s25, s3, 1
	s_cmp_le_i32 s36, s37
	s_cselect_b64 s[10:11], -1, 0
	s_add_i32 s27, s33, 2
	v_mov_b32_e32 v159, v231
	s_add_i32 s36, s3, s27
	s_add_i32 s3, s3, s33
	v_lshl_add_u64 v[130:131], s[22:23], 0, v[158:159]
	s_mov_b32 s26, 2
	s_add_i32 s37, s3, -1
	s_max_i32 s38, s35, 3
	s_mov_b32 s39, 0x28000
	s_mov_b32 s101, m0
	s_sub_i32 s100, s37, s25
	v_mbcnt_lo_u32_b32 v177, -1, 0
	v_mbcnt_hi_u32_b32 v177, -1, v177
	v_writelane_b32 v255, s101, 41
	v_add_u32_e32 v186, -2, v177
	v_ashrrev_i32_e32 v187, 1, v186
	v_and_b32_e32 v192, 1, v186
	v_add_u32_e32 v188, s27, v187
	v_sub_u32_e32 v189, s33, v187
	v_cmp_eq_u32_e32 vcc, 1, v192
	v_add_u32_e32 v189, -1, v189
	v_subrev_u32_e32 v192, s25, v186
	v_mov_b32_e32 v191, 0
	v_cndmask_b32_e32 v188, v189, v188, vcc
	v_add_u32_e32 v189, s36, v192
	v_sub_u32_e32 v192, s100, v192
	v_cmp_gt_i32_e32 vcc, s25, v186
	v_cndmask_b32_e64 v189, v192, v189, s[10:11]
	v_lshlrev_b32_e32 v190, 11, v169
	v_lshl_add_u64 v[178:179], v[190:191], 0, v[130:131]
	v_cndmask_b32_e32 v188, v189, v188, vcc
	v_cmp_gt_u32_e32 vcc, 2, v177
	v_add_u32_e32 v189, s33, v177
	v_lshlrev_b32_e32 v190, 11, v168
	v_lshl_add_u64 v[180:181], v[178:179], 0, s[96:97]
	v_cndmask_b32_e32 v177, v188, v189, vcc
	v_lshl_add_u64 v[184:185], v[190:191], 0, v[128:129]
	s_mov_b32 s99, 0
	v_lshl_add_u64 v[182:183], s[56:57], 1, v[184:185]
	v_lshl_add_u64 v[184:185], s[74:75], 1, v[184:185]
	s_branch .LBB0_320
.LBB0_319:
	s_add_i32 s6, s39, 0xfffe8000
	s_and_b32 s6, s6, 0x18000
	s_add_i32 s12, s6, 0
	s_add_i32 s6, s12, s40
	v_add_u32_e32 v76, s6, v164
	s_lshl_b32 s6, s3, 6
	v_cvt_f32_i32_e32 v80, s6
	v_add_u32_e32 v68, v76, v163
	v_add_u32_e32 v72, v76, v165
	v_add_u32_e32 v77, v76, v166
	v_add_u32_e32 v81, v76, v167
	ds_read_b128 v[64:67], v68
	ds_read_b128 v[114:117], v68 offset:4096
	ds_read_b128 v[68:71], v72
	ds_read_b128 v[124:127], v72 offset:4096
	ds_read_b128 v[72:75], v77
	ds_read_b128 v[134:137], v77 offset:4096
	ds_read_b128 v[76:79], v81
	ds_read_b128 v[120:123], v81 offset:4096
	s_cmp_lt_i32 s3, s24
	s_cselect_b64 s[6:7], -1, 0
	v_sub_f32_e32 v113, v170, v80
	v_cndmask_b32_e64 v118, -v156, v156, s[6:7]
	v_mul_f32_e32 v119, 0x41000000, v118
	v_fma_f32 v80, v118, -v113, -v155
	v_add_f32_e32 v84, v119, v80
	v_add_f32_e32 v81, v118, v80
	s_nop 0
	v_add_f32_e32 v88, v119, v84
	v_add_f32_e32 v82, v118, v81
	v_add_f32_e32 v85, v118, v84
	s_nop 0
	v_add_f32_e32 v92, v119, v88
	v_add_f32_e32 v83, v118, v82
	v_add_f32_e32 v86, v118, v85
	v_add_f32_e32 v89, v118, v88
	s_nop 0
	v_add_f32_e32 v87, v118, v86
	v_add_f32_e32 v90, v118, v89
	v_add_f32_e32 v93, v118, v92
	s_nop 0
	v_add_f32_e32 v91, v118, v90
	v_add_f32_e32 v94, v118, v93
	s_nop 0
	v_add_f32_e32 v95, v118, v94
	s_nop 0
	s_nop 1
	s_waitcnt lgkmcnt(7)
	v_mfma_f32_32x32x16_bf16 v[80:95], v[64:67], v[96:99], v[80:95]
	v_sub_f32_e32 v64, 0x42000000, v113
	v_fma_f32 v64, v118, v64, -v155
	v_add_f32_e32 v65, v118, v64
	v_add_u32_e32 v132, s12, v162
	v_add_f32_e32 v66, v118, v65
	s_nop 0
	v_add_f32_e32 v67, v118, v66
	s_waitcnt lgkmcnt(5)
	v_mfma_f32_32x32x16_bf16 v[80:95], v[68:71], v[100:103], v[80:95]
	v_add_f32_e32 v68, v119, v64
	s_nop 0
	v_add_f32_e32 v69, v118, v68
	s_nop 0
	v_add_f32_e32 v70, v118, v69
	s_nop 0
	v_add_f32_e32 v71, v118, v70
	s_waitcnt lgkmcnt(3)
	v_mfma_f32_32x32x16_bf16 v[80:95], v[72:75], v[104:107], v[80:95]
	v_add_f32_e32 v72, v119, v68
	s_nop 0
	v_add_f32_e32 v73, v118, v72
	s_nop 0
	v_add_f32_e32 v74, v118, v73
	s_nop 0
	v_add_f32_e32 v75, v118, v74
	s_waitcnt lgkmcnt(1)
	v_mfma_f32_32x32x16_bf16 v[80:95], v[76:79], v[108:111], v[80:95]
	v_add_f32_e32 v76, v119, v72
	s_nop 0
	v_add_f32_e32 v77, v118, v76
	s_nop 0
	v_add_f32_e32 v78, v118, v77
	s_nop 0
	v_add_f32_e32 v79, v118, v78
	s_nop 0
	s_nop 1
	s_nop 7
	v_exp_f32_e32 v80, v80
	ds_read_b64_tr_b16 v[138:139], v132 offset:16384
	ds_read_b64_tr_b16 v[140:141], v132 offset:16896
	ds_read_b64_tr_b16 v[142:143], v132 offset:17408
	ds_read_b64_tr_b16 v[144:145], v132 offset:17920
	v_exp_f32_e32 v81, v81
	v_exp_f32_e32 v82, v82
	v_exp_f32_e32 v83, v83
	v_add_f32_e32 v112, v112, v80
	v_add_f32_e32 v112, v81, v112
	v_add_f32_e32 v112, v82, v112
	v_add_f32_e32 v112, v83, v112
	v_mfma_f32_32x32x16_bf16 v[64:79], v[114:117], v[96:99], v[64:79]
	ds_read_b64_tr_b16 v[158:159], v132 offset:20480
	ds_read_b64_tr_b16 v[160:161], v132 offset:20992
	ds_read_b64_tr_b16 v[172:173], v132 offset:21504
	ds_read_b64_tr_b16 v[174:175], v132 offset:22016
	v_exp_f32_e32 v133, v84
	v_exp_f32_e32 v146, v85
	v_exp_f32_e32 v147, v86
	v_exp_f32_e32 v171, v87
	v_add_f32_e32 v84, v133, v112
	v_add_f32_e32 v84, v146, v84
	v_add_f32_e32 v84, v147, v84
	v_add_f32_e32 v84, v171, v84
	v_mfma_f32_32x32x16_bf16 v[64:79], v[124:127], v[100:103], v[64:79]
	ds_read_b64_tr_b16 v[124:125], v132 offset:24576
	ds_read_b64_tr_b16 v[126:127], v132 offset:25088
	ds_read_b64_tr_b16 v[116:117], v132 offset:25600
	ds_read_b64_tr_b16 v[118:119], v132 offset:26112
	v_exp_f32_e32 v88, v88
	v_exp_f32_e32 v89, v89
	v_exp_f32_e32 v90, v90
	v_exp_f32_e32 v91, v91
	v_add_f32_e32 v84, v88, v84
	v_add_f32_e32 v84, v89, v84
	v_add_f32_e32 v84, v90, v84
	v_add_f32_e32 v176, v91, v84
	v_mfma_f32_32x32x16_bf16 v[64:79], v[134:137], v[104:107], v[64:79]
	ds_read_b64_tr_b16 v[112:113], v132 offset:28672
	ds_read_b64_tr_b16 v[114:115], v132 offset:29184
	ds_read_b64_tr_b16 v[84:85], v132 offset:29696
	ds_read_b64_tr_b16 v[86:87], v132 offset:30208
	v_exp_f32_e32 v134, v92
	v_exp_f32_e32 v135, v93
	v_exp_f32_e32 v136, v94
	v_exp_f32_e32 v95, v95
	v_add_f32_e32 v92, v134, v176
	v_add_f32_e32 v92, v135, v92
	v_add_f32_e32 v92, v136, v92
	v_add_f32_e32 v137, v95, v92
	s_waitcnt lgkmcnt(14)
	v_mfma_f32_32x32x16_bf16 v[64:79], v[120:123], v[108:111], v[64:79]
	v_cvt_pk_bf16_f32 v120, v80, v81
	v_cvt_pk_bf16_f32 v121, v82, v83
	v_cvt_pk_bf16_f32 v122, v133, v146
	v_cvt_pk_bf16_f32 v123, v147, v171
	v_cvt_pk_bf16_f32 v92, v88, v89
	v_cvt_pk_bf16_f32 v93, v90, v91
	v_cvt_pk_bf16_f32 v94, v134, v135
	v_cvt_pk_bf16_f32 v95, v136, v95
	v_mfma_f32_32x32x16_bf16 v[0:15], v[138:141], v[120:123], v[0:15]
	ds_read_b64_tr_b16 v[80:81], v132 offset:18432
	ds_read_b64_tr_b16 v[82:83], v132 offset:18944
	s_nop 0
	v_exp_f32_e32 v133, v64
	v_exp_f32_e32 v138, v65
	v_add_f32_e32 v64, v137, v133
	v_add_f32_e32 v64, v138, v64
	s_waitcnt lgkmcnt(14)
	v_mfma_f32_32x32x16_bf16 v[0:15], v[142:145], v[92:95], v[0:15]
	ds_read_b64_tr_b16 v[88:89], v132 offset:19456
	ds_read_b64_tr_b16 v[90:91], v132 offset:19968
	v_exp_f32_e32 v139, v66
	v_exp_f32_e32 v140, v67
	v_add_f32_e32 v64, v139, v64
	v_add_f32_e32 v134, v140, v64
	s_waitcnt lgkmcnt(14)
	v_mfma_f32_32x32x16_bf16 v[16:31], v[158:161], v[120:123], v[16:31]
	ds_read_b64_tr_b16 v[64:65], v132 offset:22528
	ds_read_b64_tr_b16 v[66:67], v132 offset:23040
	v_exp_f32_e32 v141, v68
	v_exp_f32_e32 v142, v69
	v_add_f32_e32 v68, v141, v134
	v_add_f32_e32 v68, v142, v68
	s_waitcnt lgkmcnt(14)
	v_mfma_f32_32x32x16_bf16 v[16:31], v[172:175], v[92:95], v[16:31]
	ds_read_b64_tr_b16 v[134:135], v132 offset:23552
	ds_read_b64_tr_b16 v[136:137], v132 offset:24064
	v_exp_f32_e32 v143, v70
	v_exp_f32_e32 v144, v71
	v_add_f32_e32 v68, v143, v68
	v_add_f32_e32 v145, v144, v68
	s_waitcnt lgkmcnt(14)
	v_mfma_f32_32x32x16_bf16 v[32:47], v[124:127], v[120:123], v[32:47]
	ds_read_b64_tr_b16 v[68:69], v132 offset:26624
	ds_read_b64_tr_b16 v[70:71], v132 offset:27136
	v_exp_f32_e32 v124, v72
	v_exp_f32_e32 v125, v73
	v_add_f32_e32 v72, v124, v145
	v_add_f32_e32 v72, v125, v72
	s_waitcnt lgkmcnt(14)
	v_mfma_f32_32x32x16_bf16 v[32:47], v[116:119], v[92:95], v[32:47]
	ds_read_b64_tr_b16 v[116:117], v132 offset:27648
	ds_read_b64_tr_b16 v[118:119], v132 offset:28160
	v_exp_f32_e32 v126, v74
	v_exp_f32_e32 v127, v75
	v_add_f32_e32 v72, v126, v72
	v_add_f32_e32 v145, v127, v72
	s_waitcnt lgkmcnt(14)
	v_mfma_f32_32x32x16_bf16 v[48:63], v[112:115], v[120:123], v[48:63]
	ds_read_b64_tr_b16 v[72:73], v132 offset:30720
	ds_read_b64_tr_b16 v[74:75], v132 offset:31232
	v_exp_f32_e32 v113, v76
	v_exp_f32_e32 v114, v77
	v_add_f32_e32 v76, v113, v145
	v_add_f32_e32 v76, v114, v76
	s_waitcnt lgkmcnt(14)
	v_mfma_f32_32x32x16_bf16 v[48:63], v[84:87], v[92:95], v[48:63]
	v_exp_f32_e32 v95, v78
	ds_read_b64_tr_b16 v[84:85], v132 offset:31744
	ds_read_b64_tr_b16 v[86:87], v132 offset:32256
	v_exp_f32_e32 v115, v79
	v_add_f32_e32 v76, v95, v76
	v_add_f32_e32 v112, v115, v76
	v_cvt_pk_bf16_f32 v76, v133, v138
	v_cvt_pk_bf16_f32 v77, v139, v140
	v_cvt_pk_bf16_f32 v78, v141, v142
	v_cvt_pk_bf16_f32 v79, v143, v144
	v_cvt_pk_bf16_f32 v92, v124, v125
	v_cvt_pk_bf16_f32 v93, v126, v127
	v_cvt_pk_bf16_f32 v94, v113, v114
	v_cvt_pk_bf16_f32 v95, v95, v115
	s_bitcmp1_b32 s26, 0
	s_cbranch_scc1 .Lda_dplain
	s_cmp_ge_i32 s26, s34
	s_cbranch_scc1 .Lda_dplain
	s_add_i32 s100, s26, 2
	s_and_b32 s100, s100, 3
	s_lshl_b32 s100, s100, 15
	s_add_i32 s101, s100, s43
	s_waitcnt lgkmcnt(14)
	v_mfma_f32_32x32x16_bf16 v[0:15], v[80:83], v[76:79], v[0:15]
	s_mov_b32 m0, s101
	s_addk_i32 s101, 0x2000
	global_load_lds_dwordx4 v[186:187], off
	s_waitcnt lgkmcnt(10)
	v_mfma_f32_32x32x16_bf16 v[16:31], v[64:67], v[76:79], v[16:31]
	s_mov_b32 m0, s101
	s_add_i32 s101, s100, s45
	global_load_lds_dwordx4 v[188:189], off
	s_waitcnt lgkmcnt(6)
	v_mfma_f32_32x32x16_bf16 v[32:47], v[68:71], v[76:79], v[32:47]
	s_mov_b32 m0, s101
	s_add_i32 s101, s100, s46
	global_load_lds_dwordx4 v[190:191], off
	s_waitcnt lgkmcnt(2)
	v_mfma_f32_32x32x16_bf16 v[48:63], v[72:75], v[76:79], v[48:63]
	s_mov_b32 m0, s101
	s_add_i32 s100, s100, 0x8000
	global_load_lds_dwordx4 v[192:193], off
	s_add_i32 s101, s100, s43
	v_mfma_f32_32x32x16_bf16 v[0:15], v[88:91], v[92:95], v[0:15]
	s_mov_b32 m0, s101
	s_addk_i32 s101, 0x2000
	global_load_lds_dwordx4 v[194:195], off
	v_mfma_f32_32x32x16_bf16 v[16:31], v[134:137], v[92:95], v[16:31]
	s_mov_b32 m0, s101
	s_add_i32 s101, s100, s45
	global_load_lds_dwordx4 v[196:197], off
	v_mfma_f32_32x32x16_bf16 v[32:47], v[116:119], v[92:95], v[32:47]
	s_mov_b32 m0, s101
	s_add_i32 s101, s100, s46
	global_load_lds_dwordx4 v[198:199], off
	s_waitcnt lgkmcnt(0)
	v_mfma_f32_32x32x16_bf16 v[48:63], v[84:87], v[92:95], v[48:63]
	s_mov_b32 m0, s101
	s_nop 0
	global_load_lds_dwordx4 v[200:201], off
	s_branch .Lda_dend
.Lda_dplain:
	s_waitcnt lgkmcnt(14)
	v_mfma_f32_32x32x16_bf16 v[0:15], v[80:83], v[76:79], v[0:15]
	s_waitcnt lgkmcnt(10)
	v_mfma_f32_32x32x16_bf16 v[16:31], v[64:67], v[76:79], v[16:31]
	s_waitcnt lgkmcnt(6)
	v_mfma_f32_32x32x16_bf16 v[32:47], v[68:71], v[76:79], v[32:47]
	s_waitcnt lgkmcnt(2)
	v_mfma_f32_32x32x16_bf16 v[48:63], v[72:75], v[76:79], v[48:63]
	v_mfma_f32_32x32x16_bf16 v[0:15], v[88:91], v[92:95], v[0:15]
	v_mfma_f32_32x32x16_bf16 v[16:31], v[134:137], v[92:95], v[16:31]
	v_mfma_f32_32x32x16_bf16 v[32:47], v[116:119], v[92:95], v[32:47]
	s_waitcnt lgkmcnt(0)
	v_mfma_f32_32x32x16_bf16 v[48:63], v[84:87], v[92:95], v[48:63]
.Lda_dend:
	s_add_i32 s26, s26, 1
	s_add_i32 s37, s37, -1
	s_add_i32 s39, s39, 0x8000
	s_cmp_eq_u32 s38, s26
	s_cbranch_scc1 .Lda_exit
.LBB0_320:
	s_bitcmp1_b32 s26, 0
	s_cbranch_scc1 .Lda_tile
	s_waitcnt vmcnt(0) lgkmcnt(0)
	s_barrier
	s_cmp_ge_i32 s26, s34
	s_cbranch_scc1 .Lda_tile
	s_add_i32 s100, s26, 2
	v_readlane_b32 s98, v177, s100
	s_add_i32 s100, s26, 3
	s_add_i32 s101, s35, -1
	s_min_i32 s100, s100, s101
	s_lshl_b32 s98, s98, 17
	v_readlane_b32 s100, v177, s100
	v_lshl_add_u64 v[186:187], s[98:99], 0, v[178:179]
	v_lshl_add_u64 v[188:189], s[98:99], 0, v[180:181]
	s_lshl_b32 s100, s100, 17
	s_mov_b32 s101, 0
	v_lshl_add_u64 v[190:191], s[98:99], 0, v[182:183]
	v_lshl_add_u64 v[192:193], s[98:99], 0, v[184:185]
	v_lshl_add_u64 v[194:195], s[100:101], 0, v[178:179]
	v_lshl_add_u64 v[196:197], s[100:101], 0, v[180:181]
	v_lshl_add_u64 v[198:199], s[100:101], 0, v[182:183]
	v_lshl_add_u64 v[200:201], s[100:101], 0, v[184:185]
.Lda_tile:
	v_readlane_b32 s3, v177, s26
	s_branch .LBB0_319
.Lda_exit:
	v_readlane_b32 s101, v255, 41
	s_nop 0
	s_mov_b32 m0, s101

	.amdhsa_kernel _Z10fwd_kernel4Args
		.amdhsa_group_segment_fixed_size 0
		.amdhsa_private_segment_fixed_size 0
		.amdhsa_kernarg_size 424
		.amdhsa_user_sgpr_count 2
		.amdhsa_user_sgpr_dispatch_ptr 0
		.amdhsa_user_sgpr_queue_ptr 0
		.amdhsa_user_sgpr_kernarg_segment_ptr 1
		.amdhsa_user_sgpr_dispatch_id 0
		.amdhsa_user_sgpr_kernarg_preload_length 0
		.amdhsa_user_sgpr_kernarg_preload_offset 0
		.amdhsa_user_sgpr_private_segment_size 0
		.amdhsa_uses_dynamic_stack 0
		.amdhsa_enable_private_segment 0
		.amdhsa_system_sgpr_workgroup_id_x 1
		.amdhsa_system_sgpr_workgroup_id_y 0
		.amdhsa_system_sgpr_workgroup_id_z 0
		.amdhsa_system_sgpr_workgroup_info 0
		.amdhsa_system_vgpr_workitem_id 0
		.amdhsa_next_free_vgpr 256
		.amdhsa_next_free_sgpr 102
		.amdhsa_accum_offset 256
		.amdhsa_reserve_vcc 1
		.amdhsa_float_round_mode_32 0
		.amdhsa_float_round_mode_16_64 0
		.amdhsa_float_denorm_mode_32 3
		.amdhsa_float_denorm_mode_16_64 3
		.amdhsa_dx10_clamp 1
		.amdhsa_ieee_mode 1
		.amdhsa_fp16_overflow 0
		.amdhsa_tg_split 0
		.amdhsa_exception_fp_ieee_invalid_op 0
		.amdhsa_exception_fp_denorm_src 0
		.amdhsa_exception_fp_ieee_div_zero 0
		.amdhsa_exception_fp_ieee_overflow 0
		.amdhsa_exception_fp_ieee_underflow 0
		.amdhsa_exception_fp_ieee_inexact 0
		.amdhsa_exception_int_div_zero 0
	.end_amdhsa_kernel

amdhsa.kernels:
  - .agpr_count:     0
    .args:
      - .offset:         0
        .size:           168
        .value_kind:     by_value
      - .offset:         168
        .size:           4
        .value_kind:     hidden_block_count_x
      - .offset:         172
        .size:           4
        .value_kind:     hidden_block_count_y
      - .offset:         176
        .size:           4
        .value_kind:     hidden_block_count_z
      - .offset:         180
        .size:           2
        .value_kind:     hidden_group_size_x
      - .offset:         182
        .size:           2
        .value_kind:     hidden_group_size_y
      - .offset:         184
        .size:           2
        .value_kind:     hidden_group_size_z
      - .offset:         186
        .size:           2
        .value_kind:     hidden_remainder_x
      - .offset:         188
        .size:           2
        .value_kind:     hidden_remainder_y
      - .offset:         190
        .size:           2
        .value_kind:     hidden_remainder_z
      - .offset:         208
        .size:           8
        .value_kind:     hidden_global_offset_x
      - .offset:         216
        .size:           8
        .value_kind:     hidden_global_offset_y
      - .offset:         224
        .size:           8
        .value_kind:     hidden_global_offset_z
      - .offset:         232
        .size:           2
        .value_kind:     hidden_grid_dims
      - .offset:         288
        .size:           4
        .value_kind:     hidden_dynamic_lds_size
    .group_segment_fixed_size: 0
    .kernarg_segment_align: 8
    .kernarg_segment_size: 424
    .language:       OpenCL C
    .language_version:
      - 2
      - 0
    .max_flat_workgroup_size: 512
    .name:           _Z10fwd_kernel4Args
    .private_segment_fixed_size: 0
    .sgpr_count:     108
    .sgpr_spill_count: 314
    .symbol:         _Z10fwd_kernel4Args.kd
    .uniform_work_group_size: 1
    .uses_dynamic_stack: false
    .vgpr_count:     256
    .vgpr_spill_count: 0
    .wavefront_size: 64
